# NSA sliding-window branch: hand-written pipelined tile block for the 7 fully-inside tiles
# speedup vs baseline: 1.0325x; 1.0038x over previous
.LBB0_115:
	v_readfirstlane_b32 s11, v50
	v_readfirstlane_b32 s12, v144
	s_lshr_b32 s12, s12, 6
	s_add_u32 s13, s11, 7
	s_cmp_lt_u32 s11, s12
	s_cselect_b32 s14, 1, 0
	s_cmp_ge_u32 s13, s12
	s_cselect_b32 s15, 1, 0
	s_and_b32 s14, s14, s15
	s_cmp_lg_u32 s14, 0
	s_cbranch_scc1 .Lwinf_fast
	v_mov_b32_e32 v64, v133
	v_mov_b32_e32 v65, v132
	v_mov_b32_e32 v66, v165
	v_mov_b32_e32 v67, v164
	s_nop 1
	v_permlane16_swap_b32_e32 v133, v64
	v_permlane16_swap_b32_e32 v132, v65
	v_permlane16_swap_b32_e32 v165, v66
	v_permlane16_swap_b32_e32 v164, v67
	v_add_f32_e32 v133, v133, v64
	v_add_f32_e32 v132, v132, v65
	v_add_f32_e32 v165, v165, v66
	v_add_f32_e32 v164, v164, v67
	v_mov_b32_e32 v64, v133
	v_mov_b32_e32 v65, v132
	v_mov_b32_e32 v66, v165
	v_mov_b32_e32 v67, v164
	s_nop 1
	v_permlane32_swap_b32_e32 v133, v64
	v_permlane32_swap_b32_e32 v132, v65
	v_permlane32_swap_b32_e32 v165, v66
	v_permlane32_swap_b32_e32 v164, v67
	v_add_f32_e32 v133, v133, v64
	v_add_f32_e32 v132, v132, v65
	v_add_f32_e32 v165, v165, v66
	v_add_f32_e32 v164, v164, v67
	v_add_u32_e32 v120, s10, v208
	v_add_u32_e32 v189, v120, v149
	v_add_u32_e32 v190, v120, v155
	v_add_u32_e32 v52, v120, v210
	v_lshl_or_b32 v124, v50, 6, v145
	ds_read_b128 v[84:87], v189
	ds_read_b128 v[76:79], v190
	ds_read_b128 v[80:83], v189 offset:2048
	ds_read_b128 v[72:75], v190 offset:2048
	ds_read2st64_b64 v[48:51], v52 offset0:16 offset1:20
	v_add_u32_e32 v122, s10, v209
	v_add_u32_e32 v53, v120, v211
	ds_read2st64_b64 v[64:67], v53 offset0:16 offset1:20
	v_add_u32_e32 v174, v147, v149
	s_waitcnt lgkmcnt(0)
	v_mov_b32_e32 v68, v48
	v_add_u32_e32 v48, v122, v210
	ds_read_b64 v[60:61], v52 offset:12288
	ds_read_b64 v[62:63], v53 offset:12288
	ds_read_b64 v[56:57], v48 offset:8192
	ds_read_b128 v[52:55], v174 offset:32768
	v_add_u32_e32 v112, 0x200, v124
	v_cmp_le_i32_e32 vcc, v124, v144
	v_cmp_gt_i32_e64 s[8:9], v112, v144
	v_add_u32_e32 v112, 0x201, v124
	s_and_b64 s[22:23], vcc, s[8:9]
	v_cmp_lt_i32_e32 vcc, v124, v144
	v_cmp_gt_i32_e64 s[8:9], v112, v144
	v_or_b32_e32 v113, 2, v124
	v_add_u32_e32 v48, v122, v211
	v_add_u32_e32 v172, v147, v155
	s_and_b64 s[24:25], vcc, s[8:9]
	v_cmp_le_i32_e32 vcc, v113, v144
	v_add_u32_e32 v113, 0x202, v124
	v_mov_b32_e32 v69, v49
	v_mov_b32_e32 v70, v64
	v_mov_b32_e32 v71, v65
	v_mov_b32_e32 v64, v50
	v_mov_b32_e32 v65, v51
	ds_read_b64 v[58:59], v48 offset:8192
	ds_read_b128 v[48:51], v172 offset:32768
	v_cmp_gt_i32_e64 s[8:9], v113, v144
	v_or_b32_e32 v113, 3, v124
	s_waitcnt lgkmcnt(2)
	v_mfma_f32_16x16x32_bf16 v[104:107], v[84:87], v[52:55], 0
	s_and_b64 s[26:27], vcc, s[8:9]
	v_cmp_le_i32_e32 vcc, v113, v144
	v_add_u32_e32 v113, 0x203, v124
	v_cmp_gt_i32_e64 s[8:9], v113, v144
	v_or_b32_e32 v113, 16, v124
	v_mfma_f32_16x16x32_bf16 v[108:111], v[80:83], v[52:55], 0
	s_and_b64 s[28:29], vcc, s[8:9]
	v_cmp_le_i32_e32 vcc, v113, v144
	v_add_u32_e32 v113, 0x210, v124
	v_cmp_gt_i32_e64 s[8:9], v113, v144
	v_or_b32_e32 v113, 17, v124
	s_waitcnt lgkmcnt(0)
	v_mfma_f32_16x16x32_bf16 v[104:107], v[76:79], v[48:51], v[104:107]
	s_and_b64 s[30:31], vcc, s[8:9]
	v_cmp_le_i32_e32 vcc, v113, v144
	v_add_u32_e32 v113, 0x211, v124
	v_cmp_gt_i32_e64 s[8:9], v113, v144
	v_or_b32_e32 v113, 18, v124
	v_mfma_f32_16x16x32_bf16 v[108:111], v[72:75], v[48:51], v[108:111]
	s_and_b64 s[34:35], vcc, s[8:9]
	v_cmp_le_i32_e32 vcc, v113, v144
	v_add_u32_e32 v113, 0x212, v124
	v_cmp_gt_i32_e64 s[8:9], v113, v144
	v_or_b32_e32 v113, 19, v124
	v_cndmask_b32_e64 v104, v204, v104, s[22:23]
	v_cndmask_b32_e64 v105, v204, v105, s[24:25]
	s_and_b64 s[36:37], vcc, s[8:9]
	v_cmp_le_i32_e32 vcc, v113, v144
	v_add_u32_e32 v113, 0x213, v124
	v_max3_f32 v112, v104, s75, v105
	v_cndmask_b32_e64 v106, v204, v106, s[26:27]
	v_cndmask_b32_e64 v107, v204, v107, s[28:29]
	v_cmp_gt_i32_e64 s[8:9], v113, v144
	v_max3_f32 v112, v112, v106, v107
	v_cndmask_b32_e64 v108, v204, v108, s[30:31]
	v_cndmask_b32_e64 v109, v204, v109, s[34:35]
	s_and_b64 s[38:39], vcc, s[8:9]
	v_max3_f32 v112, v112, v108, v109
	v_cndmask_b32_e64 v110, v204, v110, s[36:37]
	v_cndmask_b32_e64 v111, v204, v111, s[38:39]
	v_max3_f32 v112, v112, v110, v111
	ds_bpermute_b32 v113, v183, v112
	v_add_u32_e32 v191, v120, v212
	v_add_u32_e32 v192, v120, v213
	v_add_u32_e32 v193, v122, v212
	v_add_u32_e32 v194, v122, v213
	s_waitcnt lgkmcnt(0)
	v_max_f32_e32 v113, v113, v113
	v_max_f32_e32 v112, v112, v113
	ds_bpermute_b32 v113, v186, v112
	s_waitcnt lgkmcnt(0)
	v_max3_f32 v151, v184, v112, v113
	v_sub_f32_e32 v112, v184, v151
	v_exp_f32_e32 v134, v112
	v_sub_f32_e32 v104, v104, v151
	v_exp_f32_e32 v104, v104
	v_sub_f32_e32 v105, v105, v151
	v_pk_mul_f32 v[116:117], v[100:101], v[134:135] op_sel_hi:[1,0]
	v_pk_mul_f32 v[100:101], v[88:89], v[134:135] op_sel_hi:[1,0]
	v_or_b32_e32 v88, 32, v124
	v_cmp_le_i32_e32 vcc, v88, v144
	v_add_u32_e32 v88, 0x220, v124
	v_cmp_gt_i32_e64 s[8:9], v88, v144
	v_or_b32_e32 v88, 33, v124
	s_and_b64 vcc, vcc, s[8:9]
	v_cmp_le_i32_e64 s[8:9], v88, v144
	v_add_u32_e32 v88, 0x221, v124
	v_cmp_gt_i32_e64 s[10:11], v88, v144
	v_or_b32_e32 v88, 34, v124
	s_and_b64 s[8:9], s[8:9], s[10:11]
	v_cmp_le_i32_e64 s[10:11], v88, v144
	v_add_u32_e32 v88, 0x222, v124
	v_cmp_gt_i32_e64 s[12:13], v88, v144
	v_or_b32_e32 v88, 35, v124
	s_and_b64 s[10:11], s[10:11], s[12:13]
	v_cmp_le_i32_e64 s[12:13], v88, v144
	v_add_u32_e32 v88, 0x223, v124
	v_cmp_gt_i32_e64 s[14:15], v88, v144
	v_or_b32_e32 v88, 48, v124
	s_and_b64 s[12:13], s[12:13], s[14:15]
	v_cmp_le_i32_e64 s[14:15], v88, v144
	v_add_u32_e32 v88, 0x230, v124
	v_cmp_gt_i32_e64 s[16:17], v88, v144
	v_or_b32_e32 v88, 49, v124
	s_and_b64 s[14:15], s[14:15], s[16:17]
	v_cmp_le_i32_e64 s[16:17], v88, v144
	v_add_u32_e32 v88, 0x231, v124
	v_exp_f32_e32 v105, v105
	v_cmp_gt_i32_e64 s[18:19], v88, v144
	v_or_b32_e32 v88, 50, v124
	s_and_b64 s[16:17], s[16:17], s[18:19]
	v_cmp_le_i32_e64 s[18:19], v88, v144
	v_add_u32_e32 v88, 0x232, v124
	v_cmp_gt_i32_e64 s[20:21], v88, v144
	v_or_b32_e32 v88, 51, v124
	v_add_f32_e32 v113, 0, v104
	v_sub_f32_e32 v106, v106, v151
	s_and_b64 s[18:19], s[18:19], s[20:21]
	v_cmp_le_i32_e64 s[20:21], v88, v144
	v_add_u32_e32 v88, 0x233, v124
	v_add_f32_e32 v167, v105, v113
	v_exp_f32_e32 v121, v106
	v_sub_f32_e32 v106, v107, v151
	v_pk_mul_f32 v[118:119], v[102:103], v[134:135] op_sel_hi:[1,0]
	v_pk_mul_f32 v[114:115], v[94:95], v[134:135] op_sel_hi:[1,0]
	v_pk_mul_f32 v[112:113], v[92:93], v[134:135] op_sel_hi:[1,0]
	v_pk_mul_f32 v[102:103], v[90:91], v[134:135] op_sel_hi:[1,0]
	v_cmp_gt_i32_e64 s[42:43], v88, v144
	ds_read_b128 v[92:95], v174 offset:40960
	ds_read_b128 v[88:91], v172 offset:40960
	v_exp_f32_e32 v123, v106
	v_sub_f32_e32 v106, v108, v151
	v_exp_f32_e32 v125, v106
	v_sub_f32_e32 v106, v109, v151
	v_exp_f32_e32 v127, v106
	v_sub_f32_e32 v106, v110, v151
	v_exp_f32_e32 v129, v106
	v_sub_f32_e32 v106, v111, v151
	v_pk_mul_f32 v[110:111], v[98:99], v[134:135] op_sel_hi:[1,0]
	v_pk_mul_f32 v[108:109], v[96:97], v[134:135] op_sel_hi:[1,0]
	s_waitcnt lgkmcnt(1)
	v_mfma_f32_16x16x32_bf16 v[96:99], v[84:87], v[92:95], 0
	v_exp_f32_e32 v131, v106
	v_cvt_pk_bf16_f32 v104, v104, v105
	v_cvt_pk_bf16_f32 v105, v121, v123
	v_mfma_f32_16x16x32_bf16 v[176:179], v[80:83], v[92:95], 0
	v_cvt_pk_bf16_f32 v106, v125, v127
	v_cvt_pk_bf16_f32 v107, v129, v131
	s_and_b64 s[20:21], s[20:21], s[42:43]
	s_waitcnt lgkmcnt(0)
	v_mfma_f32_16x16x32_bf16 v[96:99], v[76:79], v[88:91], v[96:99]
	v_mfma_f32_16x16x32_bf16 v[176:179], v[72:75], v[88:91], v[176:179]
	v_mfma_f32_16x16x32_bf16 v[108:111], v[64:67], v[104:107], v[108:111]
	s_nop 5
	v_cndmask_b32_e64 v96, v204, v96, s[22:23]
	v_cndmask_b32_e64 v97, v204, v97, s[24:25]
	v_max3_f32 v120, v96, s75, v97
	v_cndmask_b32_e64 v98, v204, v98, s[26:27]
	v_cndmask_b32_e64 v99, v204, v99, s[28:29]
	v_max3_f32 v120, v120, v98, v99
	v_cndmask_b32_e64 v124, v204, v176, s[30:31]
	v_cndmask_b32_e64 v126, v204, v177, s[34:35]
	v_max3_f32 v120, v120, v124, v126
	v_cndmask_b32_e64 v128, v204, v178, s[36:37]
	v_cndmask_b32_e64 v130, v204, v179, s[38:39]
	v_max3_f32 v120, v120, v128, v130
	ds_bpermute_b32 v122, v183, v120
	v_mfma_f32_16x16x32_bf16 v[112:115], v[60:63], v[104:107], v[112:115]
	s_waitcnt lgkmcnt(0)
	v_max_f32_e32 v122, v122, v122
	v_max_f32_e32 v120, v120, v122
	ds_bpermute_b32 v122, v186, v120
	s_waitcnt lgkmcnt(0)
	v_max3_f32 v195, v182, v120, v122
	v_sub_f32_e32 v96, v96, v195
	v_exp_f32_e32 v135, v96
	v_sub_f32_e32 v97, v97, v195
	v_exp_f32_e32 v171, v97
	v_add_f32_e32 v96, 0, v135
	v_add_f32_e32 v166, v171, v96
	v_sub_f32_e32 v96, v98, v195
	v_exp_f32_e32 v120, v96
	v_sub_f32_e32 v98, v99, v195
	v_exp_f32_e32 v122, v98
	v_sub_f32_e32 v98, v124, v195
	v_exp_f32_e32 v124, v98
	v_sub_f32_e32 v98, v126, v195
	v_exp_f32_e32 v126, v98
	v_sub_f32_e32 v98, v128, v195
	v_pk_add_f32 v[96:97], v[120:121], v[166:167]
	v_exp_f32_e32 v128, v98
	v_sub_f32_e32 v98, v130, v195
	v_pk_add_f32 v[96:97], v[122:123], v[96:97]
	v_exp_f32_e32 v130, v98
	v_pk_add_f32 v[96:97], v[124:125], v[96:97]
	s_nop 0
	v_pk_add_f32 v[96:97], v[126:127], v[96:97]
	s_nop 0
	v_pk_add_f32 v[96:97], v[128:129], v[96:97]
	s_nop 0
	v_pk_add_f32 v[96:97], v[130:131], v[96:97]
	ds_bpermute_b32 v99, v183, v97
	ds_bpermute_b32 v98, v183, v96
	s_waitcnt lgkmcnt(0)
	v_pk_add_f32 v[166:167], v[96:97], v[98:99]
	ds_bpermute_b32 v177, v186, v167
	ds_bpermute_b32 v176, v186, v166
	v_mfma_f32_16x16x32_bf16 v[96:99], v[68:71], v[104:107], v[116:119]
	v_mfma_f32_16x16x32_bf16 v[116:119], v[56:59], v[104:107], v[100:103]
	v_mov_b32_e32 v105, v134
	v_cvt_pk_bf16_f32 v102, v124, v126
	v_cvt_pk_bf16_f32 v103, v128, v130
	s_nop 1
	v_sub_f32_e32 v100, v182, v195
	v_exp_f32_e32 v104, v100
	s_waitcnt lgkmcnt(0)
	v_pk_add_f32 v[100:101], v[166:167], v[176:177]
	v_pk_mul_f32 v[38:39], v[38:39], v[104:105] op_sel_hi:[1,0]
	v_pk_fma_f32 v[166:167], v[132:133], v[104:105], v[100:101]
	v_cvt_pk_bf16_f32 v101, v120, v122
	v_pk_mul_f32 v[36:37], v[36:37], v[104:105] op_sel_hi:[1,0]
	v_pk_mul_f32 v[34:35], v[34:35], v[104:105] op_sel_hi:[1,0]
	v_pk_mul_f32 v[32:33], v[32:33], v[104:105] op_sel_hi:[1,0]
	v_pk_mul_f32 v[30:31], v[30:31], v[104:105] op_sel_hi:[1,0]
	v_pk_mul_f32 v[28:29], v[28:29], v[104:105] op_sel_hi:[1,0]
	v_pk_mul_f32 v[26:27], v[26:27], v[104:105] op_sel_hi:[1,0]
	v_pk_mul_f32 v[24:25], v[24:25], v[104:105] op_sel_hi:[1,0]
	ds_read_b128 v[120:123], v174 offset:49152
	ds_read_b128 v[104:107], v172 offset:49152
	v_cvt_pk_bf16_f32 v100, v135, v171
	s_waitcnt lgkmcnt(1)
	v_mfma_f32_16x16x32_bf16 v[124:127], v[80:83], v[120:123], 0
	v_mfma_f32_16x16x32_bf16 v[36:39], v[68:71], v[100:103], v[36:39]
	v_mfma_f32_16x16x32_bf16 v[32:35], v[64:67], v[100:103], v[32:35]
	v_mfma_f32_16x16x32_bf16 v[28:31], v[60:63], v[100:103], v[28:31]
	v_mfma_f32_16x16x32_bf16 v[24:27], v[56:59], v[100:103], v[24:27]
	v_mfma_f32_16x16x32_bf16 v[100:103], v[84:87], v[120:123], 0
	s_waitcnt lgkmcnt(0)
	v_mfma_f32_16x16x32_bf16 v[100:103], v[76:79], v[104:107], v[100:103]
	v_mfma_f32_16x16x32_bf16 v[124:127], v[72:75], v[104:107], v[124:127]
	s_nop 6
	v_cndmask_b32_e64 v100, v204, v100, s[22:23]
	v_cndmask_b32_e64 v101, v204, v101, s[24:25]
	v_max3_f32 v128, v100, s75, v101
	v_cndmask_b32_e64 v102, v204, v102, s[26:27]
	v_cndmask_b32_e64 v103, v204, v103, s[28:29]
	v_max3_f32 v128, v128, v102, v103
	v_cndmask_b32_e64 v124, v204, v124, s[30:31]
	v_cndmask_b32_e64 v125, v204, v125, s[34:35]
	v_max3_f32 v128, v128, v124, v125
	v_cndmask_b32_e64 v126, v204, v126, s[36:37]
	v_cndmask_b32_e64 v127, v204, v127, s[38:39]
	v_max3_f32 v128, v128, v126, v127
	ds_bpermute_b32 v129, v183, v128
	s_waitcnt lgkmcnt(0)
	v_max_f32_e32 v129, v129, v129
	v_max_f32_e32 v128, v128, v129
	ds_bpermute_b32 v129, v186, v128
	s_waitcnt lgkmcnt(0)
	v_max3_f32 v196, v170, v128, v129
	v_sub_f32_e32 v128, v170, v196
	v_sub_f32_e32 v102, v102, v196
	v_exp_f32_e32 v171, v102
	v_sub_f32_e32 v102, v103, v196
	v_exp_f32_e32 v182, v128
	v_exp_f32_e32 v173, v102
	v_sub_f32_e32 v102, v124, v196
	v_sub_f32_e32 v100, v100, v196
	v_exp_f32_e32 v175, v102
	v_sub_f32_e32 v102, v125, v196
	v_exp_f32_e32 v100, v100
	v_sub_f32_e32 v101, v101, v196
	v_exp_f32_e32 v177, v102
	v_sub_f32_e32 v102, v126, v196
	v_exp_f32_e32 v101, v101
	v_exp_f32_e32 v179, v102
	v_sub_f32_e32 v102, v127, v196
	v_pk_mul_f32 v[134:135], v[46:47], v[182:183] op_sel_hi:[1,0]
	v_pk_mul_f32 v[132:133], v[44:45], v[182:183] op_sel_hi:[1,0]
	v_pk_mul_f32 v[126:127], v[22:23], v[182:183] op_sel_hi:[1,0]
	v_pk_mul_f32 v[124:125], v[20:21], v[182:183] op_sel_hi:[1,0]
	v_pk_mul_f32 v[46:47], v[18:19], v[182:183] op_sel_hi:[1,0]
	v_pk_mul_f32 v[44:45], v[16:17], v[182:183] op_sel_hi:[1,0]
	ds_read_b128 v[20:23], v174 offset:57344
	ds_read_b128 v[16:19], v172 offset:57344
	v_add_f32_e32 v129, 0, v100
	v_add_f32_e32 v185, v101, v129
	v_pk_mul_f32 v[130:131], v[42:43], v[182:183] op_sel_hi:[1,0]
	v_pk_mul_f32 v[128:129], v[40:41], v[182:183] op_sel_hi:[1,0]
	s_waitcnt lgkmcnt(1)
	v_mfma_f32_16x16x32_bf16 v[40:43], v[84:87], v[20:23], 0
	v_exp_f32_e32 v181, v102
	v_cvt_pk_bf16_f32 v100, v100, v101
	v_cvt_pk_bf16_f32 v101, v171, v173
	v_mfma_f32_16x16x32_bf16 v[80:83], v[80:83], v[20:23], 0
	v_cvt_pk_bf16_f32 v102, v175, v177
	v_cvt_pk_bf16_f32 v103, v179, v181
	s_waitcnt lgkmcnt(0)
	v_mfma_f32_16x16x32_bf16 v[40:43], v[76:79], v[16:19], v[40:43]
	v_mfma_f32_16x16x32_bf16 v[72:75], v[72:75], v[16:19], v[80:83]
	v_mfma_f32_16x16x32_bf16 v[80:83], v[56:59], v[100:103], v[44:47]
	s_nop 5
	v_cndmask_b32_e64 v40, v204, v40, s[22:23]
	v_cndmask_b32_e64 v41, v204, v41, s[24:25]
	v_max3_f32 v76, v40, s75, v41
	v_cndmask_b32_e64 v42, v204, v42, s[26:27]
	v_cndmask_b32_e64 v43, v204, v43, s[28:29]
	v_max3_f32 v76, v76, v42, v43
	v_cndmask_b32_e64 v72, v204, v72, s[30:31]
	v_cndmask_b32_e64 v73, v204, v73, s[34:35]
	v_max3_f32 v76, v76, v72, v73
	v_cndmask_b32_e64 v74, v204, v74, s[36:37]
	v_cndmask_b32_e64 v75, v204, v75, s[38:39]
	v_max3_f32 v76, v76, v74, v75
	ds_bpermute_b32 v77, v183, v76
	s_waitcnt lgkmcnt(0)
	v_max_f32_e32 v77, v77, v77
	v_max_f32_e32 v76, v76, v77
	ds_bpermute_b32 v77, v186, v76
	s_waitcnt lgkmcnt(0)
	v_max3_f32 v197, v188, v76, v77
	v_sub_f32_e32 v40, v40, v197
	v_exp_f32_e32 v214, v40
	v_sub_f32_e32 v41, v41, v197
	v_exp_f32_e32 v215, v41
	v_sub_f32_e32 v44, v188, v197
	v_add_f32_e32 v40, 0, v214
	v_mfma_f32_16x16x32_bf16 v[76:79], v[60:63], v[100:103], v[124:127]
	v_add_f32_e32 v184, v215, v40
	v_sub_f32_e32 v40, v42, v197
	v_exp_f32_e32 v170, v40
	v_sub_f32_e32 v42, v43, v197
	v_exp_f32_e32 v172, v42
	v_sub_f32_e32 v42, v72, v197
	v_exp_f32_e32 v174, v42
	v_sub_f32_e32 v42, v73, v197
	v_exp_f32_e32 v176, v42
	v_sub_f32_e32 v42, v74, v197
	v_pk_add_f32 v[40:41], v[170:171], v[184:185]
	v_exp_f32_e32 v178, v42
	v_sub_f32_e32 v42, v75, v197
	v_pk_add_f32 v[40:41], v[172:173], v[40:41]
	v_exp_f32_e32 v180, v42
	v_pk_add_f32 v[40:41], v[174:175], v[40:41]
	v_mfma_f32_16x16x32_bf16 v[72:75], v[64:67], v[100:103], v[128:131]
	v_add_f32_e64 v40, v176, v40
	v_add_f32_e64 v41, v177, v41
	v_cvt_pk_bf16_f32 v46, v174, v176
	v_cvt_pk_bf16_f32 v47, v178, v180
	v_pk_add_f32 v[40:41], v[178:179], v[40:41]
	s_nop 0
	v_pk_add_f32 v[40:41], v[180:181], v[40:41]
	ds_bpermute_b32 v43, v183, v41
	ds_bpermute_b32 v42, v183, v40
	s_waitcnt lgkmcnt(0)
	v_pk_add_f32 v[84:85], v[40:41], v[42:43]
	ds_bpermute_b32 v87, v186, v85
	ds_bpermute_b32 v86, v186, v84
	v_mfma_f32_16x16x32_bf16 v[40:43], v[68:71], v[100:103], v[132:135]
	v_exp_f32_e32 v100, v44
	v_mov_b32_e32 v101, v182
	s_waitcnt lgkmcnt(0)
	v_pk_add_f32 v[44:45], v[84:85], v[86:87]
	s_nop 0
	v_pk_fma_f32 v[134:135], v[164:165], v[100:101], v[44:45]
	v_cvt_pk_bf16_f32 v44, v214, v215
	v_cvt_pk_bf16_f32 v45, v170, v172
	v_pk_mul_f32 v[14:15], v[14:15], v[100:101] op_sel_hi:[1,0]
	v_pk_mul_f32 v[12:13], v[12:13], v[100:101] op_sel_hi:[1,0]
	v_pk_mul_f32 v[10:11], v[10:11], v[100:101] op_sel_hi:[1,0]
	v_pk_mul_f32 v[8:9], v[8:9], v[100:101] op_sel_hi:[1,0]
	v_pk_mul_f32 v[6:7], v[6:7], v[100:101] op_sel_hi:[1,0]
	v_pk_mul_f32 v[4:5], v[4:5], v[100:101] op_sel_hi:[1,0]
	v_pk_mul_f32 v[2:3], v[2:3], v[100:101] op_sel_hi:[1,0]
	v_pk_mul_f32 v[0:1], v[0:1], v[100:101] op_sel_hi:[1,0]
	v_mfma_f32_16x16x32_bf16 v[12:15], v[68:71], v[44:47], v[12:15]
	v_mfma_f32_16x16x32_bf16 v[8:11], v[64:67], v[44:47], v[8:11]
	v_mfma_f32_16x16x32_bf16 v[4:7], v[60:63], v[44:47], v[4:7]
	v_mfma_f32_16x16x32_bf16 v[0:3], v[56:59], v[44:47], v[0:3]
	ds_read_b128 v[124:127], v189 offset:4096
	ds_read_b128 v[44:47], v190 offset:4096
	ds_read_b128 v[128:131], v189 offset:6144
	ds_read_b128 v[84:87], v190 offset:6144
	ds_read2st64_b64 v[56:59], v191 offset0:16 offset1:20
	ds_read2st64_b64 v[64:67], v192 offset0:16 offset1:20
	s_waitcnt lgkmcnt(1)
	v_mov_b32_e32 v68, v56
	v_mfma_f32_16x16x32_bf16 v[100:103], v[124:127], v[52:55], 0
	v_mov_b32_e32 v69, v57
	s_waitcnt lgkmcnt(0)
	v_mov_b32_e32 v70, v64
	v_mov_b32_e32 v71, v65
	v_mfma_f32_16x16x32_bf16 v[52:55], v[128:131], v[52:55], 0
	v_mov_b32_e32 v64, v58
	v_mov_b32_e32 v65, v59
	ds_read_b64 v[60:61], v191 offset:12288
	ds_read_b64 v[62:63], v192 offset:12288
	ds_read_b64 v[56:57], v193 offset:8192
	ds_read_b64 v[58:59], v194 offset:8192
	v_mfma_f32_16x16x32_bf16 v[100:103], v[44:47], v[48:51], v[100:103]
	s_waitcnt lgkmcnt(0)
	s_waitcnt vmcnt(0)
	s_barrier
	v_mfma_f32_16x16x32_bf16 v[48:51], v[84:87], v[48:51], v[52:55]
	s_nop 4
	v_cndmask_b32_e32 v52, v204, v100, vcc
	v_cndmask_b32_e64 v53, v204, v101, s[8:9]
	v_max3_f32 v54, v52, s75, v53
	v_cndmask_b32_e64 v100, v204, v102, s[10:11]
	v_cndmask_b32_e64 v101, v204, v103, s[12:13]
	v_max3_f32 v54, v54, v100, v101
	v_cndmask_b32_e64 v48, v204, v48, s[14:15]
	v_cndmask_b32_e64 v49, v204, v49, s[16:17]
	v_max3_f32 v54, v54, v48, v49
	v_cndmask_b32_e64 v50, v204, v50, s[18:19]
	v_cndmask_b32_e64 v51, v204, v51, s[20:21]
	v_max3_f32 v54, v54, v50, v51
	ds_bpermute_b32 v55, v183, v54
	s_waitcnt lgkmcnt(0)
	v_max_f32_e32 v55, v55, v55
	v_max_f32_e32 v54, v54, v55
	ds_bpermute_b32 v55, v186, v54
	s_waitcnt lgkmcnt(0)
	v_max3_f32 v184, v151, v54, v55
	v_sub_f32_e32 v52, v52, v184
	v_exp_f32_e32 v55, v52
	v_sub_f32_e32 v52, v53, v184
	v_exp_f32_e32 v165, v52
	v_sub_f32_e32 v52, v100, v184
	v_exp_f32_e32 v171, v52
	v_sub_f32_e32 v52, v101, v184
	v_mfma_f32_16x16x32_bf16 v[100:103], v[124:127], v[92:95], 0
	v_sub_f32_e32 v54, v151, v184
	v_exp_f32_e32 v173, v52
	v_exp_f32_e32 v53, v54
	v_mfma_f32_16x16x32_bf16 v[92:95], v[128:131], v[92:95], 0
	v_sub_f32_e32 v48, v48, v184
	v_exp_f32_e32 v175, v48
	v_sub_f32_e32 v48, v49, v184
	v_mfma_f32_16x16x32_bf16 v[100:103], v[44:47], v[88:91], v[100:103]
	v_exp_f32_e32 v177, v48
	v_sub_f32_e32 v48, v50, v184
	v_exp_f32_e32 v179, v48
	v_mfma_f32_16x16x32_bf16 v[88:91], v[84:87], v[88:91], v[92:95]
	v_sub_f32_e32 v48, v51, v184
	s_nop 2
	v_cndmask_b32_e32 v52, v204, v100, vcc
	v_exp_f32_e32 v181, v48
	v_cndmask_b32_e64 v92, v204, v101, s[8:9]
	v_max3_f32 v54, v52, s75, v92
	v_cndmask_b32_e64 v93, v204, v102, s[10:11]
	v_cndmask_b32_e64 v94, v204, v103, s[12:13]
	v_max3_f32 v54, v54, v93, v94
	v_cndmask_b32_e64 v95, v204, v88, s[14:15]
	v_cndmask_b32_e64 v100, v204, v89, s[16:17]
	v_max3_f32 v54, v54, v95, v100
	v_cndmask_b32_e64 v90, v204, v90, s[18:19]
	v_cndmask_b32_e64 v91, v204, v91, s[20:21]
	v_max3_f32 v54, v54, v90, v91
	ds_bpermute_b32 v88, v183, v54
	v_mov_b32_e32 v188, v53
	v_cvt_pk_bf16_f32 v48, v55, v165
	v_cvt_pk_bf16_f32 v49, v171, v173
	v_cvt_pk_bf16_f32 v50, v175, v177
	s_waitcnt lgkmcnt(0)
	v_max_f32_e32 v88, v88, v88
	v_max_f32_e32 v54, v54, v88
	ds_bpermute_b32 v88, v186, v54
	v_cvt_pk_bf16_f32 v51, v179, v181
	s_waitcnt lgkmcnt(0)
	v_max3_f32 v182, v195, v54, v88
	v_sub_f32_e32 v52, v52, v182
	v_exp_f32_e32 v54, v52
	v_sub_f32_e32 v52, v92, v182
	v_exp_f32_e32 v164, v52
	v_sub_f32_e32 v52, v93, v182
	v_exp_f32_e32 v170, v52
	v_sub_f32_e32 v52, v94, v182
	v_exp_f32_e32 v172, v52
	v_sub_f32_e32 v52, v95, v182
	v_pk_add_f32 v[88:89], v[54:55], 0 op_sel_hi:[1,0]
	v_exp_f32_e32 v174, v52
	v_sub_f32_e32 v52, v100, v182
	v_pk_add_f32 v[88:89], v[164:165], v[88:89]
	v_exp_f32_e32 v176, v52
	v_sub_f32_e32 v52, v90, v182
	v_pk_add_f32 v[88:89], v[170:171], v[88:89]
	v_exp_f32_e32 v178, v52
	v_sub_f32_e32 v52, v91, v182
	v_pk_add_f32 v[88:89], v[172:173], v[88:89]
	v_exp_f32_e32 v180, v52
	v_pk_add_f32 v[88:89], v[174:175], v[88:89]
	v_sub_f32_e32 v52, v195, v182
	v_pk_add_f32 v[88:89], v[176:177], v[88:89]
	v_exp_f32_e32 v52, v52
	v_pk_add_f32 v[88:89], v[178:179], v[88:89]
	v_pk_mul_f32 v[38:39], v[38:39], v[52:53] op_sel_hi:[1,0]
	v_pk_add_f32 v[88:89], v[180:181], v[88:89]
	ds_bpermute_b32 v91, v183, v89
	ds_bpermute_b32 v90, v183, v88
	v_pk_mul_f32 v[36:37], v[36:37], v[52:53] op_sel_hi:[1,0]
	v_pk_mul_f32 v[34:35], v[34:35], v[52:53] op_sel_hi:[1,0]
	v_pk_mul_f32 v[32:33], v[32:33], v[52:53] op_sel_hi:[1,0]
	v_pk_mul_f32 v[30:31], v[30:31], v[52:53] op_sel_hi:[1,0]
	s_waitcnt lgkmcnt(0)
	v_pk_add_f32 v[88:89], v[88:89], v[90:91]
	ds_bpermute_b32 v91, v186, v89
	ds_bpermute_b32 v90, v186, v88
	v_pk_mul_f32 v[28:29], v[28:29], v[52:53] op_sel_hi:[1,0]
	v_pk_mul_f32 v[26:27], v[26:27], v[52:53] op_sel_hi:[1,0]
	v_pk_mul_f32 v[24:25], v[24:25], v[52:53] op_sel_hi:[1,0]
	s_waitcnt lgkmcnt(0)
	v_pk_add_f32 v[132:133], v[88:89], v[90:91]
	v_pk_mul_f32 v[90:91], v[98:99], v[188:189] op_sel_hi:[1,0]
	v_pk_mul_f32 v[88:89], v[96:97], v[188:189] op_sel_hi:[1,0]
	v_pk_fma_f32 v[132:133], v[166:167], v[52:53], v[132:133]
	s_nop 0
	v_mfma_f32_16x16x32_bf16 v[100:103], v[68:71], v[48:51], v[88:91]
	s_nop 2
	v_mul_f32_e64 v90, v110, v188
	v_mul_f32_e64 v91, v111, v188
	v_pk_mul_f32 v[88:89], v[108:109], v[188:189] op_sel_hi:[1,0]
	s_nop 1
	v_mfma_f32_16x16x32_bf16 v[96:99], v[64:67], v[48:51], v[88:91]
	s_nop 2
	v_mul_f32_e64 v90, v114, v188
	v_mul_f32_e64 v91, v115, v188
	v_pk_mul_f32 v[88:89], v[112:113], v[188:189] op_sel_hi:[1,0]
	s_nop 1
	v_mfma_f32_16x16x32_bf16 v[92:95], v[60:63], v[48:51], v[88:91]
	s_nop 2
	v_mul_f32_e64 v90, v118, v188
	v_mul_f32_e64 v91, v119, v188
	v_pk_mul_f32 v[88:89], v[116:117], v[188:189] op_sel_hi:[1,0]
	s_nop 1
	v_mfma_f32_16x16x32_bf16 v[88:91], v[56:59], v[48:51], v[88:91]
	v_cvt_pk_bf16_f32 v48, v54, v164
	v_cvt_pk_bf16_f32 v49, v170, v172
	v_cvt_pk_bf16_f32 v50, v174, v176
	v_cvt_pk_bf16_f32 v51, v178, v180
	v_mfma_f32_16x16x32_bf16 v[52:55], v[128:131], v[120:123], 0
	v_mfma_f32_16x16x32_bf16 v[36:39], v[68:71], v[48:51], v[36:39]
	v_mfma_f32_16x16x32_bf16 v[32:35], v[64:67], v[48:51], v[32:35]
	v_mfma_f32_16x16x32_bf16 v[28:31], v[60:63], v[48:51], v[28:31]
	v_mfma_f32_16x16x32_bf16 v[24:27], v[56:59], v[48:51], v[24:27]
	v_mfma_f32_16x16x32_bf16 v[48:51], v[124:127], v[120:123], 0
	v_mfma_f32_16x16x32_bf16 v[48:51], v[44:47], v[104:107], v[48:51]
	v_mfma_f32_16x16x32_bf16 v[118:121], v[124:127], v[20:23], 0
	v_mfma_f32_16x16x32_bf16 v[52:55], v[84:87], v[104:107], v[52:55]
	s_nop 5
	v_cndmask_b32_e32 v48, v204, v48, vcc
	v_cndmask_b32_e64 v49, v204, v49, s[8:9]
	v_max3_f32 v104, v48, s75, v49
	v_mfma_f32_16x16x32_bf16 v[20:23], v[128:131], v[20:23], 0
	v_cndmask_b32_e64 v50, v204, v50, s[10:11]
	v_cndmask_b32_e64 v51, v204, v51, s[12:13]
	v_max3_f32 v104, v104, v50, v51
	v_mfma_f32_16x16x32_bf16 v[44:47], v[44:47], v[16:19], v[118:121]
	v_cndmask_b32_e64 v52, v204, v52, s[14:15]
	v_cndmask_b32_e64 v53, v204, v53, s[16:17]
	v_max3_f32 v104, v104, v52, v53
	v_cndmask_b32_e64 v54, v204, v54, s[18:19]
	v_cndmask_b32_e64 v106, v204, v55, s[20:21]
	v_mfma_f32_16x16x32_bf16 v[16:19], v[84:87], v[16:19], v[20:23]
	v_max3_f32 v55, v104, v54, v106
	ds_bpermute_b32 v104, v183, v55
	s_waitcnt lgkmcnt(0)
	v_max_f32_e32 v104, v104, v104
	v_cndmask_b32_e32 v20, v204, v44, vcc
	v_cndmask_b32_e64 v21, v204, v45, s[8:9]
	v_max3_f32 v22, v20, s75, v21
	v_cndmask_b32_e64 v23, v204, v46, s[10:11]
	v_cndmask_b32_e64 v44, v204, v47, s[12:13]
	v_max3_f32 v22, v22, v23, v44
	v_cndmask_b32_e64 v45, v204, v16, s[14:15]
	v_cndmask_b32_e64 v46, v204, v17, s[16:17]
	v_max3_f32 v16, v22, v45, v46
	v_cndmask_b32_e64 v18, v204, v18, s[18:19]
	v_cndmask_b32_e64 v19, v204, v19, s[20:21]
	v_max3_f32 v16, v16, v18, v19
	ds_bpermute_b32 v17, v183, v16
	v_max_f32_e32 v55, v55, v104
	ds_bpermute_b32 v104, v186, v55
	s_andn2_b64 vcc, exec, s[4:5]
	s_waitcnt lgkmcnt(1)
	v_max_f32_e32 v17, v17, v17
	v_max_f32_e32 v16, v16, v17
	s_waitcnt lgkmcnt(0)
	v_max3_f32 v170, v196, v55, v104
	ds_bpermute_b32 v17, v186, v16
	v_sub_f32_e32 v48, v48, v170
	v_exp_f32_e32 v55, v48
	v_sub_f32_e32 v48, v49, v170
	v_exp_f32_e32 v105, v48
	v_sub_f32_e32 v48, v50, v170
	v_exp_f32_e32 v107, v48
	v_sub_f32_e32 v48, v51, v170
	v_exp_f32_e32 v109, v48
	v_sub_f32_e32 v48, v52, v170
	s_waitcnt lgkmcnt(0)
	v_max3_f32 v188, v197, v16, v17
	v_exp_f32_e32 v111, v48
	v_sub_f32_e32 v48, v53, v170
	v_sub_f32_e32 v16, v20, v188
	v_sub_f32_e32 v104, v196, v170
	v_exp_f32_e32 v113, v48
	v_sub_f32_e32 v48, v54, v170
	v_exp_f32_e32 v54, v16
	v_sub_f32_e32 v20, v21, v188
	v_exp_f32_e32 v53, v104
	v_exp_f32_e32 v104, v20
	v_sub_f32_e32 v20, v23, v188
	v_exp_f32_e32 v115, v48
	v_sub_f32_e32 v48, v106, v170
	v_exp_f32_e32 v106, v20
	v_sub_f32_e32 v20, v44, v188
	v_exp_f32_e32 v108, v20
	v_sub_f32_e32 v20, v45, v188
	v_pk_add_f32 v[16:17], v[54:55], 0 op_sel_hi:[1,0]
	v_exp_f32_e32 v110, v20
	v_sub_f32_e32 v20, v46, v188
	v_pk_add_f32 v[16:17], v[104:105], v[16:17]
	v_exp_f32_e32 v112, v20
	v_sub_f32_e32 v18, v18, v188
	v_pk_add_f32 v[16:17], v[106:107], v[16:17]
	v_exp_f32_e32 v114, v18
	v_sub_f32_e32 v18, v19, v188
	v_exp_f32_e32 v117, v48
	v_pk_add_f32 v[16:17], v[108:109], v[16:17]
	v_exp_f32_e32 v116, v18
	v_pk_add_f32 v[16:17], v[110:111], v[16:17]
	v_mov_b32_e32 v86, v53
	v_pk_add_f32 v[16:17], v[112:113], v[16:17]
	v_cvt_pk_bf16_f32 v48, v55, v105
	v_cvt_pk_bf16_f32 v49, v107, v109
	v_cvt_pk_bf16_f32 v50, v111, v113
	v_cvt_pk_bf16_f32 v51, v115, v117
	s_nop 0
	v_pk_add_f32 v[16:17], v[114:115], v[16:17]
	s_nop 0
	v_pk_add_f32 v[16:17], v[116:117], v[16:17]
	ds_bpermute_b32 v19, v183, v17
	ds_bpermute_b32 v18, v183, v16
	s_waitcnt lgkmcnt(0)
	v_pk_add_f32 v[16:17], v[16:17], v[18:19]
	v_sub_f32_e32 v18, v197, v188
	ds_bpermute_b32 v19, v186, v17
	v_exp_f32_e32 v52, v18
	ds_bpermute_b32 v18, v186, v16
	v_pk_mul_f32 v[14:15], v[14:15], v[52:53] op_sel_hi:[1,0]
	v_pk_mul_f32 v[12:13], v[12:13], v[52:53] op_sel_hi:[1,0]
	s_waitcnt lgkmcnt(0)
	v_pk_add_f32 v[84:85], v[16:17], v[18:19]
	v_pk_mul_f32 v[18:19], v[42:43], v[86:87] op_sel_hi:[1,0]
	v_pk_mul_f32 v[16:17], v[40:41], v[86:87] op_sel_hi:[1,0]
	v_pk_mul_f32 v[10:11], v[10:11], v[52:53] op_sel_hi:[1,0]
	v_pk_mul_f32 v[8:9], v[8:9], v[52:53] op_sel_hi:[1,0]
	v_mfma_f32_16x16x32_bf16 v[44:47], v[68:71], v[48:51], v[16:19]
	v_mul_f32_e64 v6, v6, v52
	v_mul_f32_e64 v7, v7, v52
	v_pk_mul_f32 v[4:5], v[4:5], v[52:53] op_sel_hi:[1,0]
	v_pk_mul_f32 v[2:3], v[2:3], v[52:53] op_sel_hi:[1,0]
	v_pk_mul_f32 v[18:19], v[74:75], v[86:87] op_sel_hi:[1,0]
	v_pk_mul_f32 v[16:17], v[72:73], v[86:87] op_sel_hi:[1,0]
	v_pk_mul_f32 v[0:1], v[0:1], v[52:53] op_sel_hi:[1,0]
	v_pk_fma_f32 v[164:165], v[134:135], v[52:53], v[84:85]
	v_mfma_f32_16x16x32_bf16 v[40:43], v[64:67], v[48:51], v[16:19]
	s_nop 2
	v_mul_f32_e64 v18, v78, v86
	v_mul_f32_e64 v19, v79, v86
	v_pk_mul_f32 v[16:17], v[76:77], v[86:87] op_sel_hi:[1,0]
	s_nop 1
	v_mfma_f32_16x16x32_bf16 v[20:23], v[60:63], v[48:51], v[16:19]
	s_nop 2
	v_mul_f32_e64 v18, v82, v86
	v_mul_f32_e64 v19, v83, v86
	v_pk_mul_f32 v[16:17], v[80:81], v[86:87] op_sel_hi:[1,0]
	s_nop 1
	v_mfma_f32_16x16x32_bf16 v[16:19], v[56:59], v[48:51], v[16:19]
	v_cvt_pk_bf16_f32 v48, v54, v104
	v_cvt_pk_bf16_f32 v49, v106, v108
	v_cvt_pk_bf16_f32 v50, v110, v112
	v_cvt_pk_bf16_f32 v51, v114, v116
	s_nop 0
	v_mfma_f32_16x16x32_bf16 v[12:15], v[68:71], v[48:51], v[12:15]
	v_mfma_f32_16x16x32_bf16 v[8:11], v[64:67], v[48:51], v[8:11]
	v_mfma_f32_16x16x32_bf16 v[4:7], v[60:63], v[48:51], v[4:7]
	v_mfma_f32_16x16x32_bf16 v[0:3], v[56:59], v[48:51], v[0:3]
	v_cndmask_b32_e64 v48, 0, 1, s[6:7]
	s_nop 0
	v_readfirstlane_b32 s6, v48
	s_xor_b32 s84, s84, s6
	s_cbranch_vccz .LBB0_69
.Lwinf_latch:
	v_mov_b32_e32 v50, v187
	v_mov_b64_e32 v[48:49], v[162:163]
	s_branch .LBB0_111
.Lwinf_fast:
	s_cmp_lg_u32 s13, s12
	s_cbranch_scc1 .Lwinf_go
	v_mul_f32_e32 v133, 0x3e800000, v133
	v_mul_f32_e32 v132, 0x3e800000, v132
	v_mul_f32_e32 v165, 0x3e800000, v165
	v_mul_f32_e32 v164, 0x3e800000, v164
.Lwinf_go:
	v_add_u32_e32 v134, s10, v208
	v_add_u32_e32 v250, v134, v149
	v_add_u32_e32 v251, v134, v155
	v_add_u32_e32 v254, v147, v149
	v_add_u32_e32 v255, v147, v155
	v_add_u32_e32 v194, v134, v210
	v_add_u32_e32 v195, v134, v211
	v_add_u32_e32 v196, v134, v212
	v_add_u32_e32 v197, v134, v213
	ds_read_b128 v[52:55], v250
	ds_read_b128 v[56:59], v250 offset:2048
	ds_read_b128 v[60:63], v251
	ds_read_b128 v[64:67], v251 offset:2048
	ds_read_b128 v[104:107], v254 offset:32768
	ds_read_b128 v[108:111], v255 offset:32768
	ds_read_b128 v[112:115], v254 offset:40960
	ds_read_b128 v[116:119], v255 offset:40960
	ds_read_b64 v[68:69], v194 offset:8192
	ds_read_b64 v[70:71], v195 offset:8192
	ds_read_b64 v[72:73], v194 offset:10240
	ds_read_b64 v[74:75], v195 offset:10240
	ds_read_b64 v[76:77], v194 offset:12288
	ds_read_b64 v[78:79], v195 offset:12288
	ds_read_b64 v[80:81], v194 offset:14336
	ds_read_b64 v[82:83], v195 offset:14336
	s_waitcnt lgkmcnt(8)
	v_mfma_f32_16x16x32_bf16 v[120:123], v[52:55], v[104:107], 0
	v_mfma_f32_16x16x32_bf16 v[124:127], v[56:59], v[104:107], 0
	v_mfma_f32_16x16x32_bf16 v[128:131], v[52:55], v[112:115], 0
	v_mfma_f32_16x16x32_bf16 v[172:175], v[56:59], v[112:115], 0
	v_mfma_f32_16x16x32_bf16 v[120:123], v[60:63], v[108:111], v[120:123]
	v_mfma_f32_16x16x32_bf16 v[124:127], v[64:67], v[108:111], v[124:127]
	v_mfma_f32_16x16x32_bf16 v[128:131], v[60:63], v[116:119], v[128:131]
	v_mfma_f32_16x16x32_bf16 v[172:175], v[64:67], v[116:119], v[172:175]
	ds_read_b128 v[104:107], v254 offset:49152
	ds_read_b128 v[108:111], v255 offset:49152
	ds_read_b128 v[112:115], v254 offset:57344
	ds_read_b128 v[116:119], v255 offset:57344
	s_waitcnt lgkmcnt(0)
	v_mfma_f32_16x16x32_bf16 v[176:179], v[52:55], v[104:107], 0
	v_max3_f32 v84, v120, s75, v121
	v_max3_f32 v84, v84, v122, v123
	v_max3_f32 v84, v84, v124, v125
	v_max3_f32 v84, v84, v126, v127
	v_max3_f32 v85, v128, s75, v129
	v_max3_f32 v85, v85, v130, v131
	v_max3_f32 v85, v85, v172, v173
	v_max3_f32 v85, v85, v174, v175
	v_mov_b32_e32 v86, v84
	v_mov_b32_e32 v87, v85
	s_nop 1
	v_permlane16_swap_b32_e32 v84, v86
	v_permlane16_swap_b32_e32 v85, v87
	v_max_f32_e32 v84, v84, v86
	v_max_f32_e32 v85, v85, v87
	v_mov_b32_e32 v86, v84
	v_mov_b32_e32 v87, v85
	s_nop 1
	v_permlane32_swap_b32_e32 v84, v86
	v_permlane32_swap_b32_e32 v85, v87
	v_mfma_f32_16x16x32_bf16 v[190:193], v[56:59], v[104:107], 0
	v_max3_f32 v84, v184, v84, v86
	v_sub_f32_e32 v246, v184, v84
	v_mov_b32_e32 v248, v84
	v_exp_f32_e32 v246, v246
	v_mov_b32_e32 v184, v84
	v_max3_f32 v85, v182, v85, v87
	v_sub_f32_e32 v247, v182, v85
	v_mov_b32_e32 v249, v85
	v_exp_f32_e32 v247, v247
	v_mov_b32_e32 v182, v85
	v_mfma_f32_16x16x32_bf16 v[238:241], v[52:55], v[112:115], 0
	v_sub_f32_e32 v120, v120, v248
	v_sub_f32_e32 v121, v121, v248
	v_sub_f32_e32 v122, v122, v248
	v_sub_f32_e32 v123, v123, v248
	v_sub_f32_e32 v124, v124, v248
	v_sub_f32_e32 v125, v125, v248
	v_sub_f32_e32 v126, v126, v248
	v_sub_f32_e32 v127, v127, v248
	v_sub_f32_e32 v128, v128, v249
	v_sub_f32_e32 v129, v129, v249
	v_mfma_f32_16x16x32_bf16 v[242:245], v[56:59], v[112:115], 0
	v_sub_f32_e32 v130, v130, v249
	v_sub_f32_e32 v131, v131, v249
	v_sub_f32_e32 v172, v172, v249
	v_sub_f32_e32 v173, v173, v249
	v_sub_f32_e32 v174, v174, v249
	v_sub_f32_e32 v175, v175, v249
	v_exp_f32_e32 v120, v120
	v_exp_f32_e32 v121, v121
	v_exp_f32_e32 v122, v122
	v_mfma_f32_16x16x32_bf16 v[176:179], v[60:63], v[108:111], v[176:179]
	v_exp_f32_e32 v123, v123
	v_exp_f32_e32 v124, v124
	v_exp_f32_e32 v125, v125
	v_exp_f32_e32 v126, v126
	v_exp_f32_e32 v127, v127
	v_exp_f32_e32 v128, v128
	v_exp_f32_e32 v129, v129
	v_exp_f32_e32 v130, v130
	v_exp_f32_e32 v131, v131
	v_exp_f32_e32 v172, v172
	v_mfma_f32_16x16x32_bf16 v[190:193], v[64:67], v[108:111], v[190:193]
	v_exp_f32_e32 v173, v173
	v_exp_f32_e32 v174, v174
	v_exp_f32_e32 v175, v175
	v_add_f32_e32 v84, v120, v121
	v_add_f32_e32 v86, v122, v123
	v_add_f32_e32 v84, v84, v86
	v_add_f32_e32 v86, v124, v125
	v_add_f32_e32 v84, v84, v86
	v_add_f32_e32 v86, v126, v127
	v_add_f32_e32 v84, v84, v86
	v_mfma_f32_16x16x32_bf16 v[238:241], v[60:63], v[116:119], v[238:241]
	v_fma_f32 v133, v133, v246, v84
	v_add_f32_e32 v85, v128, v129
	v_add_f32_e32 v87, v130, v131
	v_add_f32_e32 v85, v85, v87
	v_add_f32_e32 v87, v172, v173
	v_add_f32_e32 v85, v85, v87
	v_add_f32_e32 v87, v174, v175
	v_add_f32_e32 v85, v85, v87
	v_fma_f32 v132, v132, v247, v85
	v_cvt_pk_bf16_f32 v120, v120, v121
	v_mfma_f32_16x16x32_bf16 v[242:245], v[64:67], v[116:119], v[242:245]
	ds_read_b128 v[52:55], v250 offset:4096
	ds_read_b128 v[56:59], v250 offset:6144
	ds_read_b128 v[60:63], v251 offset:4096
	ds_read_b128 v[64:67], v251 offset:6144
	ds_read_b128 v[104:107], v254 offset:32768
	ds_read_b128 v[108:111], v255 offset:32768
	ds_read_b128 v[112:115], v254 offset:40960
	ds_read_b128 v[116:119], v255 offset:40960
	v_cvt_pk_bf16_f32 v121, v122, v123
	v_cvt_pk_bf16_f32 v122, v124, v125
	v_cvt_pk_bf16_f32 v123, v126, v127
	v_cvt_pk_bf16_f32 v128, v128, v129
	v_cvt_pk_bf16_f32 v129, v130, v131
	v_cvt_pk_bf16_f32 v130, v172, v173
	v_cvt_pk_bf16_f32 v131, v174, v175
	v_cmp_neq_f32_e32 vcc, 1.0, v246
	s_nop 1
	s_cbranch_vccz .Lwinf_r0
	v_mul_f32_e32 v100, v100, v246
	v_mul_f32_e32 v101, v101, v246
	v_mul_f32_e32 v102, v102, v246
	v_mul_f32_e32 v103, v103, v246
	v_mul_f32_e32 v96, v96, v246
	v_mul_f32_e32 v97, v97, v246
	v_mul_f32_e32 v98, v98, v246
	v_mul_f32_e32 v99, v99, v246
	v_mul_f32_e32 v92, v92, v246
	v_mul_f32_e32 v93, v93, v246
	v_mul_f32_e32 v94, v94, v246
	v_mul_f32_e32 v95, v95, v246
	v_mul_f32_e32 v88, v88, v246
	v_mul_f32_e32 v89, v89, v246
	v_mul_f32_e32 v90, v90, v246
	v_mul_f32_e32 v91, v91, v246
.Lwinf_r0:
	v_cmp_neq_f32_e32 vcc, 1.0, v247
	s_nop 1
	s_cbranch_vccz .Lwinf_r1
	v_mul_f32_e32 v36, v36, v247
	v_mul_f32_e32 v37, v37, v247
	v_mul_f32_e32 v38, v38, v247
	v_mul_f32_e32 v39, v39, v247
	v_mul_f32_e32 v32, v32, v247
	v_mul_f32_e32 v33, v33, v247
	v_mul_f32_e32 v34, v34, v247
	v_mul_f32_e32 v35, v35, v247
	v_mul_f32_e32 v28, v28, v247
	v_mul_f32_e32 v29, v29, v247
	v_mul_f32_e32 v30, v30, v247
	v_mul_f32_e32 v31, v31, v247
	v_mul_f32_e32 v24, v24, v247
	v_mul_f32_e32 v25, v25, v247
	v_mul_f32_e32 v26, v26, v247
	v_mul_f32_e32 v27, v27, v247
.Lwinf_r1:
	s_waitcnt lgkmcnt(12)
	v_mfma_f32_16x16x32_bf16 v[100:103], v[68:71], v[120:123], v[100:103]
	v_max3_f32 v84, v176, s75, v177
	v_max3_f32 v84, v84, v178, v179
	v_max3_f32 v84, v84, v190, v191
	v_max3_f32 v84, v84, v192, v193
	v_max3_f32 v85, v238, s75, v239
	v_mfma_f32_16x16x32_bf16 v[36:39], v[68:71], v[128:131], v[36:39]
	v_max3_f32 v85, v85, v240, v241
	v_max3_f32 v85, v85, v242, v243
	v_max3_f32 v85, v85, v244, v245
	v_mov_b32_e32 v86, v84
	v_mov_b32_e32 v87, v85
	s_nop 1
	v_permlane16_swap_b32_e32 v84, v86
	v_permlane16_swap_b32_e32 v85, v87
	v_max_f32_e32 v84, v84, v86
	v_max_f32_e32 v85, v85, v87
	v_mov_b32_e32 v86, v84
	v_mov_b32_e32 v87, v85
	s_nop 1
	v_permlane32_swap_b32_e32 v84, v86
	v_permlane32_swap_b32_e32 v85, v87
	v_mfma_f32_16x16x32_bf16 v[96:99], v[72:75], v[120:123], v[96:99]
	v_max3_f32 v84, v170, v84, v86
	v_sub_f32_e32 v246, v170, v84
	v_mov_b32_e32 v248, v84
	v_exp_f32_e32 v246, v246
	v_mov_b32_e32 v170, v84
	v_mfma_f32_16x16x32_bf16 v[32:35], v[72:75], v[128:131], v[32:35]
	v_max3_f32 v85, v188, v85, v87
	v_sub_f32_e32 v247, v188, v85
	v_mov_b32_e32 v249, v85
	v_exp_f32_e32 v247, v247
	v_mov_b32_e32 v188, v85
	v_mfma_f32_16x16x32_bf16 v[92:95], v[76:79], v[120:123], v[92:95]
	v_sub_f32_e32 v176, v176, v248
	v_sub_f32_e32 v177, v177, v248
	v_sub_f32_e32 v178, v178, v248
	v_sub_f32_e32 v179, v179, v248
	v_sub_f32_e32 v190, v190, v248
	v_mfma_f32_16x16x32_bf16 v[28:31], v[76:79], v[128:131], v[28:31]
	v_sub_f32_e32 v191, v191, v248
	v_sub_f32_e32 v192, v192, v248
	v_sub_f32_e32 v193, v193, v248
	v_sub_f32_e32 v238, v238, v249
	v_sub_f32_e32 v239, v239, v249
	v_mfma_f32_16x16x32_bf16 v[88:91], v[80:83], v[120:123], v[88:91]
	v_sub_f32_e32 v240, v240, v249
	v_sub_f32_e32 v241, v241, v249
	v_sub_f32_e32 v242, v242, v249
	v_sub_f32_e32 v243, v243, v249
	v_sub_f32_e32 v244, v244, v249
	v_mfma_f32_16x16x32_bf16 v[24:27], v[80:83], v[128:131], v[24:27]
	v_sub_f32_e32 v245, v245, v249
	v_exp_f32_e32 v176, v176
	v_exp_f32_e32 v177, v177
	v_exp_f32_e32 v178, v178
	s_waitcnt lgkmcnt(0)
	v_mfma_f32_16x16x32_bf16 v[120:123], v[52:55], v[104:107], 0
	v_exp_f32_e32 v179, v179
	v_exp_f32_e32 v190, v190
	v_exp_f32_e32 v191, v191
	v_exp_f32_e32 v192, v192
	v_exp_f32_e32 v193, v193
	v_mfma_f32_16x16x32_bf16 v[124:127], v[56:59], v[104:107], 0
	v_exp_f32_e32 v238, v238
	v_exp_f32_e32 v239, v239
	v_exp_f32_e32 v240, v240
	v_exp_f32_e32 v241, v241
	v_exp_f32_e32 v242, v242
	v_mfma_f32_16x16x32_bf16 v[128:131], v[52:55], v[112:115], 0
	v_exp_f32_e32 v243, v243
	v_exp_f32_e32 v244, v244
	v_exp_f32_e32 v245, v245
	v_add_f32_e32 v84, v176, v177
	v_add_f32_e32 v86, v178, v179
	v_mfma_f32_16x16x32_bf16 v[172:175], v[56:59], v[112:115], 0
	v_add_f32_e32 v84, v84, v86
	v_add_f32_e32 v86, v190, v191
	v_add_f32_e32 v84, v84, v86
	v_add_f32_e32 v86, v192, v193
	v_add_f32_e32 v84, v84, v86
	v_mfma_f32_16x16x32_bf16 v[120:123], v[60:63], v[108:111], v[120:123]
	v_fma_f32 v165, v165, v246, v84
	v_add_f32_e32 v85, v238, v239
	v_add_f32_e32 v87, v240, v241
	v_add_f32_e32 v85, v85, v87
	v_add_f32_e32 v87, v242, v243
	v_mfma_f32_16x16x32_bf16 v[124:127], v[64:67], v[108:111], v[124:127]
	v_add_f32_e32 v85, v85, v87
	v_add_f32_e32 v87, v244, v245
	v_add_f32_e32 v85, v85, v87
	v_fma_f32 v164, v164, v247, v85
	v_cvt_pk_bf16_f32 v176, v176, v177
	v_mfma_f32_16x16x32_bf16 v[128:131], v[60:63], v[116:119], v[128:131]
	v_cvt_pk_bf16_f32 v177, v178, v179
	v_cvt_pk_bf16_f32 v178, v190, v191
	v_cvt_pk_bf16_f32 v179, v192, v193
	v_cvt_pk_bf16_f32 v238, v238, v239
	v_cvt_pk_bf16_f32 v239, v240, v241
	v_mfma_f32_16x16x32_bf16 v[172:175], v[64:67], v[116:119], v[172:175]
	ds_read_b128 v[104:107], v254 offset:49152
	ds_read_b128 v[108:111], v255 offset:49152
	ds_read_b128 v[112:115], v254 offset:57344
	ds_read_b128 v[116:119], v255 offset:57344
	v_cvt_pk_bf16_f32 v240, v242, v243
	v_cvt_pk_bf16_f32 v241, v244, v245
	v_cmp_neq_f32_e32 vcc, 1.0, v246
	s_nop 1
	s_cbranch_vccz .Lwinf_r2
	v_mul_f32_e32 v44, v44, v246
	v_mul_f32_e32 v45, v45, v246
	v_mul_f32_e32 v46, v46, v246
	v_mul_f32_e32 v47, v47, v246
	v_mul_f32_e32 v40, v40, v246
	v_mul_f32_e32 v41, v41, v246
	v_mul_f32_e32 v42, v42, v246
	v_mul_f32_e32 v43, v43, v246
	v_mul_f32_e32 v20, v20, v246
	v_mul_f32_e32 v21, v21, v246
	v_mul_f32_e32 v22, v22, v246
	v_mul_f32_e32 v23, v23, v246
	v_mul_f32_e32 v16, v16, v246
	v_mul_f32_e32 v17, v17, v246
	v_mul_f32_e32 v18, v18, v246
	v_mul_f32_e32 v19, v19, v246
.Lwinf_r2:
	v_cmp_neq_f32_e32 vcc, 1.0, v247
	s_nop 1
	s_cbranch_vccz .Lwinf_r3
	v_mul_f32_e32 v12, v12, v247
	v_mul_f32_e32 v13, v13, v247
	v_mul_f32_e32 v14, v14, v247
	v_mul_f32_e32 v15, v15, v247
	v_mul_f32_e32 v8, v8, v247
	v_mul_f32_e32 v9, v9, v247
	v_mul_f32_e32 v10, v10, v247
	v_mul_f32_e32 v11, v11, v247
	v_mul_f32_e32 v4, v4, v247
	v_mul_f32_e32 v5, v5, v247
	v_mul_f32_e32 v6, v6, v247
	v_mul_f32_e32 v7, v7, v247
	v_mul_f32_e32 v0, v0, v247
	v_mul_f32_e32 v1, v1, v247
	v_mul_f32_e32 v2, v2, v247
	v_mul_f32_e32 v3, v3, v247
.Lwinf_r3:
	v_mfma_f32_16x16x32_bf16 v[44:47], v[68:71], v[176:179], v[44:47]
	v_max3_f32 v84, v120, s75, v121
	v_max3_f32 v84, v84, v122, v123
	v_max3_f32 v84, v84, v124, v125
	v_max3_f32 v84, v84, v126, v127
	v_max3_f32 v85, v128, s75, v129
	v_mfma_f32_16x16x32_bf16 v[12:15], v[68:71], v[238:241], v[12:15]
	v_max3_f32 v85, v85, v130, v131
	v_max3_f32 v85, v85, v172, v173
	v_max3_f32 v85, v85, v174, v175
	v_mov_b32_e32 v86, v84
	v_mov_b32_e32 v87, v85
	s_nop 1
	v_permlane16_swap_b32_e32 v84, v86
	v_permlane16_swap_b32_e32 v85, v87
	v_max_f32_e32 v84, v84, v86
	v_max_f32_e32 v85, v85, v87
	v_mov_b32_e32 v86, v84
	v_mov_b32_e32 v87, v85
	s_nop 1
	v_permlane32_swap_b32_e32 v84, v86
	v_permlane32_swap_b32_e32 v85, v87
	v_mfma_f32_16x16x32_bf16 v[40:43], v[72:75], v[176:179], v[40:43]
	v_max3_f32 v84, v184, v84, v86
	v_sub_f32_e32 v246, v184, v84
	v_mov_b32_e32 v248, v84
	v_exp_f32_e32 v246, v246
	v_mov_b32_e32 v184, v84
	v_mfma_f32_16x16x32_bf16 v[8:11], v[72:75], v[238:241], v[8:11]
	v_max3_f32 v85, v182, v85, v87
	v_sub_f32_e32 v247, v182, v85
	v_mov_b32_e32 v249, v85
	v_exp_f32_e32 v247, v247
	v_mov_b32_e32 v182, v85
	v_mfma_f32_16x16x32_bf16 v[20:23], v[76:79], v[176:179], v[20:23]
	v_sub_f32_e32 v120, v120, v248
	v_sub_f32_e32 v121, v121, v248
	v_sub_f32_e32 v122, v122, v248
	v_sub_f32_e32 v123, v123, v248
	v_sub_f32_e32 v124, v124, v248
	v_mfma_f32_16x16x32_bf16 v[4:7], v[76:79], v[238:241], v[4:7]
	v_sub_f32_e32 v125, v125, v248
	v_sub_f32_e32 v126, v126, v248
	v_sub_f32_e32 v127, v127, v248
	v_sub_f32_e32 v128, v128, v249
	v_sub_f32_e32 v129, v129, v249
	v_mfma_f32_16x16x32_bf16 v[16:19], v[80:83], v[176:179], v[16:19]
	v_sub_f32_e32 v130, v130, v249
	v_sub_f32_e32 v131, v131, v249
	v_sub_f32_e32 v172, v172, v249
	v_sub_f32_e32 v173, v173, v249
	v_sub_f32_e32 v174, v174, v249
	v_mfma_f32_16x16x32_bf16 v[0:3], v[80:83], v[238:241], v[0:3]
	v_sub_f32_e32 v175, v175, v249
	v_exp_f32_e32 v120, v120
	v_exp_f32_e32 v121, v121
	v_exp_f32_e32 v122, v122
	ds_read_b64 v[68:69], v196 offset:8192
	ds_read_b64 v[70:71], v197 offset:8192
	ds_read_b64 v[72:73], v196 offset:10240
	ds_read_b64 v[74:75], v197 offset:10240
	ds_read_b64 v[76:77], v196 offset:12288
	ds_read_b64 v[78:79], v197 offset:12288
	ds_read_b64 v[80:81], v196 offset:14336
	ds_read_b64 v[82:83], v197 offset:14336
	s_waitcnt lgkmcnt(8)
	v_mfma_f32_16x16x32_bf16 v[176:179], v[52:55], v[104:107], 0
	v_exp_f32_e32 v123, v123
	v_exp_f32_e32 v124, v124
	v_exp_f32_e32 v125, v125
	v_exp_f32_e32 v126, v126
	v_exp_f32_e32 v127, v127
	v_mfma_f32_16x16x32_bf16 v[190:193], v[56:59], v[104:107], 0
	v_exp_f32_e32 v128, v128
	v_exp_f32_e32 v129, v129
	v_exp_f32_e32 v130, v130
	v_exp_f32_e32 v131, v131
	v_exp_f32_e32 v172, v172
	v_mfma_f32_16x16x32_bf16 v[238:241], v[52:55], v[112:115], 0
	v_exp_f32_e32 v173, v173
	v_exp_f32_e32 v174, v174
	v_exp_f32_e32 v175, v175
	v_add_f32_e32 v84, v120, v121
	v_add_f32_e32 v86, v122, v123
	v_mfma_f32_16x16x32_bf16 v[242:245], v[56:59], v[112:115], 0
	v_add_f32_e32 v84, v84, v86
	v_add_f32_e32 v86, v124, v125
	v_add_f32_e32 v84, v84, v86
	v_add_f32_e32 v86, v126, v127
	v_add_f32_e32 v84, v84, v86
	v_mfma_f32_16x16x32_bf16 v[176:179], v[60:63], v[108:111], v[176:179]
	v_fma_f32 v133, v133, v246, v84
	v_add_f32_e32 v85, v128, v129
	v_add_f32_e32 v87, v130, v131
	v_add_f32_e32 v85, v85, v87
	v_add_f32_e32 v87, v172, v173
	v_mfma_f32_16x16x32_bf16 v[190:193], v[64:67], v[108:111], v[190:193]
	v_add_f32_e32 v85, v85, v87
	v_add_f32_e32 v87, v174, v175
	v_add_f32_e32 v85, v85, v87
	v_fma_f32 v132, v132, v247, v85
	v_cvt_pk_bf16_f32 v120, v120, v121
	v_mfma_f32_16x16x32_bf16 v[238:241], v[60:63], v[116:119], v[238:241]
	v_cvt_pk_bf16_f32 v121, v122, v123
	v_cvt_pk_bf16_f32 v122, v124, v125
	v_cvt_pk_bf16_f32 v123, v126, v127
	v_cvt_pk_bf16_f32 v128, v128, v129
	v_cvt_pk_bf16_f32 v129, v130, v131
	v_mfma_f32_16x16x32_bf16 v[242:245], v[64:67], v[116:119], v[242:245]
	v_cvt_pk_bf16_f32 v130, v172, v173
	v_cvt_pk_bf16_f32 v131, v174, v175
	v_cmp_neq_f32_e32 vcc, 1.0, v246
	s_nop 1
	s_cbranch_vccz .Lwinf_r4
	v_mul_f32_e32 v100, v100, v246
	v_mul_f32_e32 v101, v101, v246
	v_mul_f32_e32 v102, v102, v246
	v_mul_f32_e32 v103, v103, v246
	v_mul_f32_e32 v96, v96, v246
	v_mul_f32_e32 v97, v97, v246
	v_mul_f32_e32 v98, v98, v246
	v_mul_f32_e32 v99, v99, v246
	v_mul_f32_e32 v92, v92, v246
	v_mul_f32_e32 v93, v93, v246
	v_mul_f32_e32 v94, v94, v246
	v_mul_f32_e32 v95, v95, v246
	v_mul_f32_e32 v88, v88, v246
	v_mul_f32_e32 v89, v89, v246
	v_mul_f32_e32 v90, v90, v246
	v_mul_f32_e32 v91, v91, v246

.Lwinf_r5:
	s_waitcnt lgkmcnt(0)
	v_mfma_f32_16x16x32_bf16 v[100:103], v[68:71], v[120:123], v[100:103]
	v_max3_f32 v84, v176, s75, v177
	v_max3_f32 v84, v84, v178, v179
	v_max3_f32 v84, v84, v190, v191
	v_max3_f32 v84, v84, v192, v193
	v_max3_f32 v85, v238, s75, v239
	v_max3_f32 v85, v85, v240, v241
	v_max3_f32 v85, v85, v242, v243
	v_max3_f32 v85, v85, v244, v245
	v_mov_b32_e32 v86, v84
	v_mov_b32_e32 v87, v85
	s_nop 1
	v_permlane16_swap_b32_e32 v84, v86
	v_permlane16_swap_b32_e32 v85, v87
	v_max_f32_e32 v84, v84, v86
	v_max_f32_e32 v85, v85, v87
	v_mov_b32_e32 v86, v84
	v_mov_b32_e32 v87, v85
	s_nop 1
	v_permlane32_swap_b32_e32 v84, v86
	v_permlane32_swap_b32_e32 v85, v87
	v_mfma_f32_16x16x32_bf16 v[36:39], v[68:71], v[128:131], v[36:39]
	v_max3_f32 v84, v170, v84, v86
	v_sub_f32_e32 v246, v170, v84
	v_mov_b32_e32 v248, v84
	v_exp_f32_e32 v246, v246
	v_mov_b32_e32 v170, v84
	v_max3_f32 v85, v188, v85, v87
	v_sub_f32_e32 v247, v188, v85
	v_mov_b32_e32 v249, v85
	v_exp_f32_e32 v247, v247
	v_mov_b32_e32 v188, v85
	v_mfma_f32_16x16x32_bf16 v[96:99], v[72:75], v[120:123], v[96:99]
	v_sub_f32_e32 v176, v176, v248
	v_sub_f32_e32 v177, v177, v248
	v_sub_f32_e32 v178, v178, v248
	v_sub_f32_e32 v179, v179, v248
	v_sub_f32_e32 v190, v190, v248
	v_sub_f32_e32 v191, v191, v248
	v_sub_f32_e32 v192, v192, v248
	v_sub_f32_e32 v193, v193, v248
	v_sub_f32_e32 v238, v238, v249
	v_sub_f32_e32 v239, v239, v249
	v_mfma_f32_16x16x32_bf16 v[32:35], v[72:75], v[128:131], v[32:35]
	v_sub_f32_e32 v240, v240, v249
	v_sub_f32_e32 v241, v241, v249
	v_sub_f32_e32 v242, v242, v249
	v_sub_f32_e32 v243, v243, v249
	v_sub_f32_e32 v244, v244, v249
	v_sub_f32_e32 v245, v245, v249
	v_exp_f32_e32 v176, v176
	v_exp_f32_e32 v177, v177
	v_exp_f32_e32 v178, v178
	v_mfma_f32_16x16x32_bf16 v[92:95], v[76:79], v[120:123], v[92:95]
	v_exp_f32_e32 v179, v179
	v_exp_f32_e32 v190, v190
	v_exp_f32_e32 v191, v191
	v_exp_f32_e32 v192, v192
	v_exp_f32_e32 v193, v193
	v_exp_f32_e32 v238, v238
	v_exp_f32_e32 v239, v239
	v_exp_f32_e32 v240, v240
	v_exp_f32_e32 v241, v241
	v_exp_f32_e32 v242, v242
	v_mfma_f32_16x16x32_bf16 v[28:31], v[76:79], v[128:131], v[28:31]
	v_exp_f32_e32 v243, v243
	v_exp_f32_e32 v244, v244
	v_exp_f32_e32 v245, v245
	v_add_f32_e32 v84, v176, v177
	v_add_f32_e32 v86, v178, v179
	v_add_f32_e32 v84, v84, v86
	v_add_f32_e32 v86, v190, v191
	v_add_f32_e32 v84, v84, v86
	v_add_f32_e32 v86, v192, v193
	v_add_f32_e32 v84, v84, v86
	v_mfma_f32_16x16x32_bf16 v[88:91], v[80:83], v[120:123], v[88:91]
	v_fma_f32 v165, v165, v246, v84
	v_add_f32_e32 v85, v238, v239
	v_add_f32_e32 v87, v240, v241
	v_add_f32_e32 v85, v85, v87
	v_add_f32_e32 v87, v242, v243
	v_add_f32_e32 v85, v85, v87
	v_add_f32_e32 v87, v244, v245
	v_add_f32_e32 v85, v85, v87
	v_fma_f32 v164, v164, v247, v85
	v_cvt_pk_bf16_f32 v176, v176, v177
	v_mfma_f32_16x16x32_bf16 v[24:27], v[80:83], v[128:131], v[24:27]
	v_cvt_pk_bf16_f32 v177, v178, v179
	v_cvt_pk_bf16_f32 v178, v190, v191
	v_cvt_pk_bf16_f32 v179, v192, v193
	v_cvt_pk_bf16_f32 v238, v238, v239
	v_cvt_pk_bf16_f32 v239, v240, v241
	v_cvt_pk_bf16_f32 v240, v242, v243
	v_cvt_pk_bf16_f32 v241, v244, v245
	v_cmp_neq_f32_e32 vcc, 1.0, v246
	s_nop 1
	s_cbranch_vccz .Lwinf_r6
	v_mul_f32_e32 v44, v44, v246
	v_mul_f32_e32 v45, v45, v246
	v_mul_f32_e32 v46, v46, v246
	v_mul_f32_e32 v47, v47, v246
	v_mul_f32_e32 v40, v40, v246
	v_mul_f32_e32 v41, v41, v246
	v_mul_f32_e32 v42, v42, v246
	v_mul_f32_e32 v43, v43, v246
	v_mul_f32_e32 v20, v20, v246
	v_mul_f32_e32 v21, v21, v246
	v_mul_f32_e32 v22, v22, v246
	v_mul_f32_e32 v23, v23, v246
	v_mul_f32_e32 v16, v16, v246
	v_mul_f32_e32 v17, v17, v246
	v_mul_f32_e32 v18, v18, v246
	v_mul_f32_e32 v19, v19, v246

.Lwinf_r7:
	v_mfma_f32_16x16x32_bf16 v[44:47], v[68:71], v[176:179], v[44:47]
	v_mfma_f32_16x16x32_bf16 v[12:15], v[68:71], v[238:241], v[12:15]
	v_mfma_f32_16x16x32_bf16 v[40:43], v[72:75], v[176:179], v[40:43]
	v_mfma_f32_16x16x32_bf16 v[8:11], v[72:75], v[238:241], v[8:11]
	v_mfma_f32_16x16x32_bf16 v[20:23], v[76:79], v[176:179], v[20:23]
	v_mfma_f32_16x16x32_bf16 v[4:7], v[76:79], v[238:241], v[4:7]
	v_mfma_f32_16x16x32_bf16 v[16:19], v[80:83], v[176:179], v[16:19]
	v_mfma_f32_16x16x32_bf16 v[0:3], v[80:83], v[238:241], v[0:3]
	s_waitcnt lgkmcnt(0)
	s_waitcnt vmcnt(0)
	s_barrier
	s_andn2_b64 vcc, exec, s[4:5]
	s_cmp_lg_u64 s[6:7], 0
	s_cselect_b32 s6, 1, 0
	s_xor_b32 s84, s84, s6
	s_cbranch_vccz .LBB0_69
	s_branch .Lwinf_latch
